# MIX: bf16 pair packing via v_cvt_pk_bf16_f32 instead of the bfe/add3 bit trick (34 sites)
# speedup vs baseline: 1.0101x; 1.0050x over previous
; #define LAS __attribute__((address_space(3)))
; __device__ __forceinline__ unsigned pk2(float lo, float hi) { return f2bf(lo) | (f2bf(hi) << 16); }
; #define BF8_TO_F32(vw, lo, hi) const f32x4 lo = {bflo(vw.x), bfhi(vw.x), bflo(vw.y), bfhi(vw.y)}, hi = {bflo(vw.z), bfhi(vw.z), bflo(vw.w), bfhi(vw.w)}
; __device__ __forceinline__ void mix_phase(LAS unsigned char* lds, const Params& p, const int layer) {
;     ...
;                 for (int i = 0; i < 2; ++i) {
;                     const int rl = (tid >> 4) + 32 * i, r = r0N + rl, c = c0 + q16 * 8, t = (r - NP) & 7, bs = (r - NP) >> 3;
;                     f32x4 x0 = *(const LAS f32x4*)(CWL + q16 * 8), x1 = *(const LAS f32x4*)(CWL + q16 * 8 + 4);
; #pragma unroll
;                     for (int k = 0; k < 4; ++k) { const int jb = 3 - k;
;                         const f32x4 w0 = *(const LAS f32x4*)(CWL + (k + 1) * 128 + q16 * 8), w1 = *(const LAS f32x4*)(CWL + (k + 1) * 128 + q16 * 8 + 4);
;                         if (jb <= t) { const v4u vw = *(const v4u*)(PROJ + (size_t)(r - jb) * NC + C_UB + c); BF8_TO_F32(vw, a0, a1); x0 += w0 * a0; x1 += w1 * a1; }
;                         else { const float* sp = sconv + ((size_t)bs * 3 + (3 + t - jb)) * LW + c; x0 += w0 * *(const f32x4*)sp; x1 += w1 * *(const f32x4*)(sp + 4); }
;                     }
;                     *(LAS f32x4*)(XCN + rl * 132 + q16 * 8) = x0; *(LAS f32x4*)(XCN + rl * 132 + q16 * 8 + 4) = x1;
;                     v4u o; o.x = pk2(x0[0], x0[1]); o.y = pk2(x0[2], x0[3]); o.z = pk2(x1[0], x1[1]); o.w = pk2(x1[2], x1[3]);
;                     *(LAS v4u*)(AtN + rl * 136 + q16 * 8) = o;
;                 }
.LBB0_387:
	s_or_b64 exec, exec, s[46:47]
	s_waitcnt lgkmcnt(0)
	s_waitcnt vmcnt(1)
	v_pk_fma_f32 v[66:67], v[74:75], v[86:87], v[66:67]
	v_mov_b64_e32 v[74:75], s[74:75]
	v_mad_i64_i32 v[74:75], s[2:3], v133, s25, v[74:75]
	v_lshl_add_u64 v[74:75], v[74:75], 0, v[0:1]
	s_movk_i32 s2, 0x1000
	s_waitcnt vmcnt(0)
	v_pk_fma_f32 v[72:73], v[80:81], v[84:85], v[72:73]
	v_pk_fma_f32 v[70:71], v[78:79], v[82:83], v[70:71]
	v_pk_fma_f32 v[68:69], v[76:77], v[88:89], v[68:69]
	v_add_co_u32_e32 v74, vcc, s2, v74
	v_pk_fma_f32 v[72:73], v[96:97], v[100:101], v[72:73]
	v_pk_fma_f32 v[70:71], v[94:95], v[98:99], v[70:71]
	v_pk_fma_f32 v[68:69], v[92:93], v[104:105], v[68:69]
	v_pk_fma_f32 v[66:67], v[90:91], v[102:103], v[66:67]
	v_addc_co_u32_e32 v75, vcc, 0, v75, vcc
	v_pk_fma_f32 v[78:79], v[112:113], v[116:117], v[72:73]
	v_pk_fma_f32 v[80:81], v[110:111], v[114:115], v[70:71]
	v_pk_fma_f32 v[82:83], v[108:109], v[120:121], v[68:69]
	v_pk_fma_f32 v[84:85], v[106:107], v[118:119], v[66:67]
	ds_read_b128 v[66:69], v125 offset:2048
	ds_read_b128 v[70:73], v125 offset:2064
	global_load_dwordx4 v[74:77], v[74:75], off
	s_movk_i32 s2, 0x210
	s_xor_b64 s[46:47], s[44:45], -1
	s_mov_b64 s[44:45], 0
	s_andn2_b64 vcc, exec, s[46:47]
	s_waitcnt lgkmcnt(0)
	s_waitcnt vmcnt(0)
	v_lshlrev_b32_e32 v88, 16, v74
	v_and_b32_e32 v89, 0xffff0000, v74
	v_lshlrev_b32_e32 v74, 16, v75
	v_and_b32_e32 v75, 0xffff0000, v75
	v_pk_fma_f32 v[66:67], v[66:67], v[88:89], v[80:81]
	v_lshlrev_b32_e32 v86, 16, v76
	v_and_b32_e32 v87, 0xffff0000, v76
	v_lshlrev_b32_e32 v76, 16, v77
	v_and_b32_e32 v77, 0xffff0000, v77
	v_pk_fma_f32 v[68:69], v[68:69], v[74:75], v[78:79]
	v_mad_u64_u32 v[74:75], s[2:3], v127, s2, v[124:125]
	v_pk_fma_f32 v[72:73], v[72:73], v[76:77], v[82:83]
	v_pk_fma_f32 v[70:71], v[70:71], v[86:87], v[84:85]
	ds_write_b128 v74, v[66:69]
	ds_write_b128 v74, v[70:73] offset:16
	v_cvt_pk_bf16_f32 v66, v66, v67
	v_cvt_pk_bf16_f32 v67, v68, v69
	v_cvt_pk_bf16_f32 v68, v70, v71
	s_movk_i32 s2, 0x110
	v_cvt_pk_bf16_f32 v69, v72, v73
	v_mad_u64_u32 v[70:71], s[2:3], v127, s2, v[126:127]
	s_mov_b32 s2, 32
	ds_write_b128 v70, v[66:69]
	s_cbranch_vccz .LBB0_400

; #define LAS __attribute__((address_space(3)))
; __device__ __forceinline__ unsigned pk2(float lo, float hi) { return f2bf(lo) | (f2bf(hi) << 16); }
; #define BF8_TO_F32(vw, lo, hi) const f32x4 lo = {bflo(vw.x), bfhi(vw.x), bflo(vw.y), bfhi(vw.y)}, hi = {bflo(vw.z), bfhi(vw.z), bflo(vw.w), bfhi(vw.w)}
; __device__ __forceinline__ void mix_phase(LAS unsigned char* lds, const Params& p, const int layer) {
;     ...
;             if (prtN) {
;                 const f32x4 cb0 = *(const LAS f32x4*)(CWL + q16 * 8), cb1 = *(const LAS f32x4*)(CWL + q16 * 8 + 4);
; #pragma unroll
;                 for (int i = 0; i < 2; ++i) {
;                     const int rl = (tid >> 4) + 32 * i, t = (r0N + rl) & 2047;
;                     f32x4 x0 = cb0, x1 = cb1;
; #pragma unroll
;                     for (int k = 0; k < 4; ++k) { const float f = ((3 - k) <= t) ? 1.0f : 0.0f;
;                         const f32x4 w0 = *(const LAS f32x4*)(CWL + (k + 1) * 128 + q16 * 8), w1 = *(const LAS f32x4*)(CWL + (k + 1) * 128 + q16 * 8 + 4);
;                         BF8_TO_F32(pre[i][k], a0, a1); x0 += w0 * (a0 * f); x1 += w1 * (a1 * f); }
;                     *(LAS f32x4*)(XCN + rl * 132 + q16 * 8) = x0; *(LAS f32x4*)(XCN + rl * 132 + q16 * 8 + 4) = x1;
;                     v4u o; o.x = pk2(x0[0], x0[1]); o.y = pk2(x0[2], x0[3]); o.z = pk2(x1[0], x1[1]); o.w = pk2(x1[2], x1[3]);
;                     *(LAS v4u*)(AtN + rl * 136 + q16 * 8) = o;
;                 }
.LBB0_401:
	s_movk_i32 s2, 0x110
	s_and_b64 vcc, exec, s[20:21]
	v_lshlrev_b32_e32 v138, 1, v134
	v_mul_lo_u32 v141, v226, s2
	s_cbranch_vccz .LBB0_403
	v_lshl_add_u32 v0, v134, 2, 0
	v_readlane_b32 s2, v249, 2
	v_add_u32_e32 v100, 0x21400, v0
	ds_read_b128 v[66:69], v100
	ds_read_b128 v[70:73], v100 offset:16
	v_add_u32_e32 v101, s2, v226
	v_and_b32_e32 v102, 0x7ff, v101
	ds_read_b128 v[74:77], v100 offset:512
	ds_read_b128 v[78:81], v100 offset:528
	v_cmp_gt_u32_e32 vcc, 3, v102
	s_waitcnt vmcnt(7)
	v_lshlrev_b32_e32 v84, 16, v34
	v_and_b32_e32 v85, 0xffff0000, v34
	v_cndmask_b32_e64 v82, 1.0, 0, vcc
	v_lshlrev_b32_e32 v86, 16, v35
	v_and_b32_e32 v87, 0xffff0000, v35
	v_lshlrev_b32_e32 v88, 16, v36
	v_and_b32_e32 v89, 0xffff0000, v36
	v_lshlrev_b32_e32 v90, 16, v37
	v_and_b32_e32 v91, 0xffff0000, v37
	v_pk_mul_f32 v[86:87], v[82:83], v[86:87] op_sel_hi:[0,1]
	v_pk_mul_f32 v[84:85], v[82:83], v[84:85] op_sel_hi:[0,1]
	s_waitcnt lgkmcnt(1)
	v_pk_fma_f32 v[84:85], v[84:85], v[74:75], v[66:67]
	v_pk_fma_f32 v[86:87], v[86:87], v[76:77], v[68:69]
	v_pk_mul_f32 v[74:75], v[82:83], v[90:91] op_sel_hi:[0,1]
	v_pk_mul_f32 v[76:77], v[82:83], v[88:89] op_sel_hi:[0,1]
	s_waitcnt lgkmcnt(0)
	v_pk_fma_f32 v[82:83], v[76:77], v[78:79], v[70:71]
	v_pk_fma_f32 v[88:89], v[74:75], v[80:81], v[72:73]
	ds_read_b128 v[74:77], v100 offset:1024
	ds_read_b128 v[78:81], v100 offset:1040
	v_cmp_gt_u32_e32 vcc, 2, v102
	s_waitcnt vmcnt(6)
	v_lshlrev_b32_e32 v92, 16, v38
	v_and_b32_e32 v93, 0xffff0000, v38
	v_cndmask_b32_e64 v90, 1.0, 0, vcc
	v_lshlrev_b32_e32 v94, 16, v39
	v_and_b32_e32 v95, 0xffff0000, v39
	v_lshlrev_b32_e32 v96, 16, v40
	v_and_b32_e32 v97, 0xffff0000, v40
	v_lshlrev_b32_e32 v98, 16, v41
	v_and_b32_e32 v99, 0xffff0000, v41
	v_pk_mul_f32 v[92:93], v[90:91], v[92:93] op_sel_hi:[0,1]
	v_pk_mul_f32 v[94:95], v[90:91], v[94:95] op_sel_hi:[0,1]
	s_waitcnt lgkmcnt(1)
	v_pk_fma_f32 v[86:87], v[94:95], v[76:77], v[86:87]
	v_pk_fma_f32 v[84:85], v[92:93], v[74:75], v[84:85]
	v_pk_mul_f32 v[74:75], v[90:91], v[96:97] op_sel_hi:[0,1]
	v_pk_mul_f32 v[76:77], v[90:91], v[98:99] op_sel_hi:[0,1]
	s_waitcnt lgkmcnt(0)
	v_pk_fma_f32 v[88:89], v[76:77], v[80:81], v[88:89]
	v_pk_fma_f32 v[82:83], v[74:75], v[78:79], v[82:83]
	ds_read_b128 v[74:77], v100 offset:1536
	ds_read_b128 v[78:81], v100 offset:1552
	v_cmp_eq_u32_e32 vcc, 0, v102
	s_waitcnt vmcnt(5)
	v_lshlrev_b32_e32 v92, 16, v42
	v_and_b32_e32 v93, 0xffff0000, v42
	v_cndmask_b32_e64 v90, 1.0, 0, vcc
	v_lshlrev_b32_e32 v94, 16, v43
	v_and_b32_e32 v95, 0xffff0000, v43
	v_lshlrev_b32_e32 v96, 16, v44
	v_and_b32_e32 v97, 0xffff0000, v44
	v_lshlrev_b32_e32 v98, 16, v45
	v_and_b32_e32 v99, 0xffff0000, v45
	v_pk_mul_f32 v[94:95], v[90:91], v[94:95] op_sel_hi:[0,1]
	v_pk_mul_f32 v[92:93], v[90:91], v[92:93] op_sel_hi:[0,1]
	s_waitcnt lgkmcnt(1)
	v_pk_fma_f32 v[84:85], v[92:93], v[74:75], v[84:85]
	v_pk_fma_f32 v[86:87], v[94:95], v[76:77], v[86:87]
	v_pk_mul_f32 v[74:75], v[90:91], v[98:99] op_sel_hi:[0,1]
	v_pk_mul_f32 v[76:77], v[90:91], v[96:97] op_sel_hi:[0,1]
	s_waitcnt lgkmcnt(0)
	v_pk_fma_f32 v[82:83], v[76:77], v[78:79], v[82:83]
	v_pk_fma_f32 v[88:89], v[74:75], v[80:81], v[88:89]
	ds_read_b128 v[74:77], v100 offset:2048
	ds_read_b128 v[78:81], v100 offset:2064
	s_waitcnt vmcnt(4)
	v_lshlrev_b32_e32 v90, 16, v46
	v_and_b32_e32 v91, 0xffff0000, v46
	v_lshlrev_b32_e32 v92, 16, v47
	v_and_b32_e32 v93, 0xffff0000, v47
	v_lshlrev_b32_e32 v94, 16, v48
	v_and_b32_e32 v95, 0xffff0000, v48
	s_waitcnt lgkmcnt(1)
	v_pk_fma_f32 v[74:75], v[74:75], v[90:91], v[84:85]
	s_movk_i32 s2, 0x210
	v_lshlrev_b32_e32 v96, 16, v49
	v_and_b32_e32 v97, 0xffff0000, v49
	v_pk_fma_f32 v[76:77], v[76:77], v[92:93], v[86:87]
	s_waitcnt lgkmcnt(0)
; #define LAS __attribute__((address_space(3)))
; __device__ __forceinline__ unsigned pk2(float lo, float hi) { return f2bf(lo) | (f2bf(hi) << 16); }
; #define BF8_TO_F32(vw, lo, hi) const f32x4 lo = {bflo(vw.x), bfhi(vw.x), bflo(vw.y), bfhi(vw.y)}, hi = {bflo(vw.z), bfhi(vw.z), bflo(vw.w), bfhi(vw.w)}
; __device__ __forceinline__ void mix_phase(LAS unsigned char* lds, const Params& p, const int layer) {
;     ...
;                 for (int i = 0; i < 2; ++i) {
;                     const int rl = (tid >> 4) + 32 * i, t = (r0N + rl) & 2047;
;                     f32x4 x0 = cb0, x1 = cb1;
; #pragma unroll
;                     for (int k = 0; k < 4; ++k) { const float f = ((3 - k) <= t) ? 1.0f : 0.0f;
;                         const f32x4 w0 = *(const LAS f32x4*)(CWL + (k + 1) * 128 + q16 * 8), w1 = *(const LAS f32x4*)(CWL + (k + 1) * 128 + q16 * 8 + 4);
;                         BF8_TO_F32(pre[i][k], a0, a1); x0 += w0 * (a0 * f); x1 += w1 * (a1 * f); }
;                     *(LAS f32x4*)(XCN + rl * 132 + q16 * 8) = x0; *(LAS f32x4*)(XCN + rl * 132 + q16 * 8 + 4) = x1;
;                     v4u o; o.x = pk2(x0[0], x0[1]); o.y = pk2(x0[2], x0[3]); o.z = pk2(x1[0], x1[1]); o.w = pk2(x1[2], x1[3]);
;                     *(LAS v4u*)(AtN + rl * 136 + q16 * 8) = o;
;                 }
	v_pk_fma_f32 v[78:79], v[78:79], v[94:95], v[82:83]
	v_mad_u64_u32 v[82:83], s[2:3], v226, s2, v[0:1]
	v_pk_fma_f32 v[80:81], v[80:81], v[96:97], v[88:89]
	ds_write_b128 v82, v[74:77]
	ds_write_b128 v82, v[78:81] offset:16
	v_cvt_pk_bf16_f32 v74, v74, v75
	v_cvt_pk_bf16_f32 v75, v76, v77
	v_cvt_pk_bf16_f32 v76, v78, v79
	v_cvt_pk_bf16_f32 v77, v80, v81
	v_readlane_b32 s2, v248, 5
	v_add_u32_e32 v0, 32, v101
	v_add3_u32 v83, s2, v138, v141
	ds_write_b128 v83, v[74:77]
	v_and_b32_e32 v92, 0x7ff, v0
	ds_read_b128 v[74:77], v100 offset:512
	ds_read_b128 v[78:81], v100 offset:528
	v_cmp_gt_u32_e32 vcc, 3, v92
	s_waitcnt vmcnt(3)
	v_lshlrev_b32_e32 v84, 16, v50
	v_and_b32_e32 v85, 0xffff0000, v50
	v_cndmask_b32_e64 v0, 1.0, 0, vcc
	v_lshlrev_b32_e32 v86, 16, v51
	v_and_b32_e32 v87, 0xffff0000, v51
	v_lshlrev_b32_e32 v88, 16, v52
	v_and_b32_e32 v89, 0xffff0000, v52
	v_lshlrev_b32_e32 v90, 16, v53
	v_and_b32_e32 v91, 0xffff0000, v53
	v_pk_mul_f32 v[84:85], v[0:1], v[84:85] op_sel_hi:[0,1]
	v_pk_mul_f32 v[86:87], v[0:1], v[86:87] op_sel_hi:[0,1]
	s_waitcnt lgkmcnt(1)
	v_pk_fma_f32 v[76:77], v[86:87], v[76:77], v[68:69]
	v_pk_fma_f32 v[74:75], v[84:85], v[74:75], v[66:67]
	v_pk_mul_f32 v[66:67], v[0:1], v[88:89] op_sel_hi:[0,1]
	v_pk_mul_f32 v[68:69], v[0:1], v[90:91] op_sel_hi:[0,1]
	s_waitcnt lgkmcnt(0)
	v_pk_fma_f32 v[80:81], v[68:69], v[80:81], v[72:73]
	v_pk_fma_f32 v[78:79], v[66:67], v[78:79], v[70:71]
	ds_read_b128 v[66:69], v100 offset:1024
	ds_read_b128 v[70:73], v100 offset:1040
	v_cmp_gt_u32_e32 vcc, 2, v92
	s_waitcnt vmcnt(2)
	v_lshlrev_b32_e32 v84, 16, v54
	v_and_b32_e32 v85, 0xffff0000, v54
	v_cndmask_b32_e64 v0, 1.0, 0, vcc
	v_lshlrev_b32_e32 v86, 16, v55
	v_and_b32_e32 v87, 0xffff0000, v55
	v_lshlrev_b32_e32 v88, 16, v56
	v_and_b32_e32 v89, 0xffff0000, v56
	v_lshlrev_b32_e32 v90, 16, v57
	v_and_b32_e32 v91, 0xffff0000, v57
	v_pk_mul_f32 v[86:87], v[0:1], v[86:87] op_sel_hi:[0,1]
	v_pk_mul_f32 v[84:85], v[0:1], v[84:85] op_sel_hi:[0,1]
	s_waitcnt lgkmcnt(1)
	v_pk_fma_f32 v[74:75], v[84:85], v[66:67], v[74:75]
	v_pk_fma_f32 v[76:77], v[86:87], v[68:69], v[76:77]
	v_pk_mul_f32 v[66:67], v[0:1], v[90:91] op_sel_hi:[0,1]
	v_pk_mul_f32 v[68:69], v[0:1], v[88:89] op_sel_hi:[0,1]
	s_waitcnt lgkmcnt(0)
	v_pk_fma_f32 v[78:79], v[68:69], v[70:71], v[78:79]
	v_pk_fma_f32 v[80:81], v[66:67], v[72:73], v[80:81]
	ds_read_b128 v[66:69], v100 offset:1536
	ds_read_b128 v[70:73], v100 offset:1552
	v_cmp_eq_u32_e32 vcc, 0, v92
	s_waitcnt vmcnt(1)
	v_lshlrev_b32_e32 v84, 16, v58
	v_and_b32_e32 v85, 0xffff0000, v58
	v_cndmask_b32_e64 v0, 1.0, 0, vcc
	v_lshlrev_b32_e32 v86, 16, v59
	v_and_b32_e32 v87, 0xffff0000, v59
	v_lshlrev_b32_e32 v88, 16, v60
	v_and_b32_e32 v89, 0xffff0000, v60
	v_lshlrev_b32_e32 v90, 16, v61
	v_and_b32_e32 v91, 0xffff0000, v61
	v_pk_mul_f32 v[84:85], v[0:1], v[84:85] op_sel_hi:[0,1]
	v_pk_mul_f32 v[86:87], v[0:1], v[86:87] op_sel_hi:[0,1]
	s_waitcnt lgkmcnt(1)
	v_pk_fma_f32 v[76:77], v[86:87], v[68:69], v[76:77]
	v_pk_fma_f32 v[74:75], v[84:85], v[66:67], v[74:75]
	v_pk_mul_f32 v[66:67], v[0:1], v[88:89] op_sel_hi:[0,1]
	v_pk_mul_f32 v[68:69], v[0:1], v[90:91] op_sel_hi:[0,1]
	s_waitcnt lgkmcnt(0)
	v_pk_fma_f32 v[80:81], v[68:69], v[72:73], v[80:81]
	v_pk_fma_f32 v[78:79], v[66:67], v[70:71], v[78:79]
	ds_read_b128 v[66:69], v100 offset:2048
	ds_read_b128 v[70:73], v100 offset:2064
	s_waitcnt vmcnt(0)
	v_lshlrev_b32_e32 v84, 16, v62
	v_and_b32_e32 v85, 0xffff0000, v62
	v_lshlrev_b32_e32 v86, 16, v63
	v_and_b32_e32 v87, 0xffff0000, v63
	s_waitcnt lgkmcnt(1)
	v_pk_fma_f32 v[66:67], v[66:67], v[84:85], v[74:75]
	v_lshlrev_b32_e32 v88, 16, v64
	v_and_b32_e32 v89, 0xffff0000, v64
	v_lshlrev_b32_e32 v90, 16, v65
	v_and_b32_e32 v91, 0xffff0000, v65
	v_pk_fma_f32 v[68:69], v[68:69], v[86:87], v[76:77]
	s_waitcnt lgkmcnt(0)
	v_pk_fma_f32 v[70:71], v[70:71], v[88:89], v[78:79]
	v_pk_fma_f32 v[72:73], v[72:73], v[90:91], v[80:81]
	ds_write_b128 v82, v[66:69] offset:16896
	ds_write_b128 v82, v[70:73] offset:16912
	v_cvt_pk_bf16_f32 v66, v66, v67
	v_cvt_pk_bf16_f32 v67, v68, v69
	v_cvt_pk_bf16_f32 v68, v70, v71
	v_cvt_pk_bf16_f32 v69, v72, v73
	ds_write_b128 v83, v[66:69] offset:8704

; #define LAS __attribute__((address_space(3)))
; __device__ __forceinline__ unsigned pk2(float lo, float hi) { return f2bf(lo) | (f2bf(hi) << 16); }
; __device__ __forceinline__ float bflo(unsigned w) { return __uint_as_float(w << 16); }
; __device__ __forceinline__ float bfhi(unsigned w) { return __uint_as_float(w & 0xffff0000u); }
; __device__ __forceinline__ void mix_phase(LAS unsigned char* lds, const Params& p, const int layer) {
;     ...
;                 for (int m = 0; m < 4; ++m)
; #pragma unroll
;                     for (int jj = 0; jj < 4; ++jj) XC[(m * 16 + fq * 4 + jj) * 132 + cw + fr] = hl[m][jj];
;                 __syncthreads();
;             {
;                 const int row = yrow, c16 = yc16; const size_t r = (size_t)(r0 + row);
;                 const v4u g0 = sgc0, g1 = sgc1;
;                 const f32x4 h0 = *(const LAS f32x4*)(XC + row * 132 + c16), h1 = *(const LAS f32x4*)(XC + row * 132 + c16 + 4),
;                             h2 = *(const LAS f32x4*)(XC + row * 132 + c16 + 8), h3 = *(const LAS f32x4*)(XC + row * 132 + c16 + 12);
;                 v4u o0, o1;
;                 o0.x = pk2(h0[0] * bflo(g0.x), h0[1] * bfhi(g0.x)); o0.y = pk2(h0[2] * bflo(g0.y), h0[3] * bfhi(g0.y)); o0.z = pk2(h1[0] * bflo(g0.z), h1[1] * bfhi(g0.z)); o0.w = pk2(h1[2] * bflo(g0.w), h1[3] * bfhi(g0.w));
;                 o1.x = pk2(h2[0] * bflo(g1.x), h2[1] * bfhi(g1.x)); o1.y = pk2(h2[2] * bflo(g1.y), h2[3] * bfhi(g1.y)); o1.z = pk2(h3[0] * bflo(g1.z), h3[1] * bfhi(g1.z)); o1.w = pk2(h3[2] * bflo(g1.w), h3[3] * bfhi(g1.w));
;                 bf16* yp = (bf16*)(ws + WS_YA) + r * KCAT + PW + c0 + c16;
;                 *(v4u*)yp = o0; *(v4u*)(yp + 8) = o1;
.Lpf_skip:
	v_add_u32_e32 v0, 0x400, v151
	ds_write2_b32 v0, v156, v157 offset0:8 offset1:140
	v_add_u32_e32 v0, 0x2000, v151
	ds_write2_b32 v0, v78, v79 offset0:64 offset1:196
	v_add_u32_e32 v0, 0x2400, v151
	ds_write2_b32 v0, v168, v169 offset0:72 offset1:204
	v_add_u32_e32 v0, 0x4200, v151
	ds_write2_b32 v0, v76, v77 offset1:132
	v_add_u32_e32 v0, 0x4600, v151
	ds_write2_b32 v0, v180, v181 offset0:8 offset1:140
	v_add_u32_e32 v0, 0x6200, v151
	ds_write2_b32 v0, v74, v75 offset0:64 offset1:196
	v_add_u32_e32 v0, 0x6600, v151
	ds_write2_b32 v0, v190, v191 offset0:72 offset1:204
	v_lshlrev_b32_e32 v0, 2, v140
	v_add3_u32 v0, s6, v234, v0
	ds_write2_b32 v151, v80, v81 offset1:132
	s_waitcnt lgkmcnt(0)
	s_barrier
	ds_read_b128 v[74:77], v0
	ds_read_b128 v[78:81], v0 offset:16
	ds_read_b128 v[82:85], v0 offset:32
	ds_read_b128 v[86:89], v0 offset:48
	v_lshlrev_b32_e32 v91, 16, v71
	v_lshlrev_b32_e32 v90, 16, v70
	s_waitcnt lgkmcnt(0)
	v_mov_b32_e32 v93, v76
	v_and_b32_e32 v71, 0xffff0000, v71
	v_and_b32_e32 v70, 0xffff0000, v70
	v_mov_b32_e32 v76, v75
	v_mov_b32_e32 v92, v74
	v_pk_mul_f32 v[70:71], v[76:77], v[70:71]
	v_lshlrev_b32_e32 v75, 16, v73
	v_lshlrev_b32_e32 v74, 16, v72
	v_mov_b32_e32 v77, v80
	v_and_b32_e32 v73, 0xffff0000, v73
	v_and_b32_e32 v72, 0xffff0000, v72
	v_mov_b32_e32 v80, v79
	v_mov_b32_e32 v76, v78
	v_pk_mul_f32 v[72:73], v[80:81], v[72:73]
	v_pk_mul_f32 v[90:91], v[92:93], v[90:91]
	v_pk_mul_f32 v[74:75], v[76:77], v[74:75]
	v_bfe_u32 v0, v73, 16, 1
	v_bfe_u32 v76, v72, 16, 1
	v_bfe_u32 v77, v71, 16, 1
	v_bfe_u32 v78, v70, 16, 1
	v_add3_u32 v71, v71, v77, s26
	v_add3_u32 v72, v72, v76, s26
	v_add3_u32 v0, v73, v0, s26
	v_bfe_u32 v73, v90, 16, 1
	v_bfe_u32 v76, v91, 16, 1
	v_bfe_u32 v77, v74, 16, 1
	v_add3_u32 v70, v70, v78, s26
	v_bfe_u32 v78, v75, 16, 1
	v_add3_u32 v74, v74, v77, s26
	v_add3_u32 v76, v91, v76, s26
	v_add3_u32 v73, v90, v73, s26
	v_add3_u32 v75, v75, v78, s26
	v_lshrrev_b32_e32 v77, 16, v73
	v_lshrrev_b32_e32 v76, 16, v76
	v_lshrrev_b32_e32 v74, 16, v74
	v_lshrrev_b32_e32 v73, 16, v75
	v_and_or_b32 v72, v72, s24, v74
	v_and_or_b32 v71, v71, s24, v76
	v_and_or_b32 v70, v70, s24, v77
	v_lshlrev_b32_e32 v75, 16, v67
	v_lshlrev_b32_e32 v74, 16, v66
	v_mov_b32_e32 v76, v82
	v_mov_b32_e32 v77, v84
	v_pk_mul_f32 v[74:75], v[76:77], v[74:75]
	v_lshlrev_b32_e32 v77, 16, v69
	v_lshlrev_b32_e32 v76, 16, v68
	v_mov_b32_e32 v79, v88
	v_and_b32_e32 v69, 0xffff0000, v69
	v_and_b32_e32 v68, 0xffff0000, v68
	v_mov_b32_e32 v88, v87
	v_mov_b32_e32 v78, v86
	v_pk_mul_f32 v[68:69], v[88:89], v[68:69]
	v_and_or_b32 v73, v0, s24, v73
	v_and_b32_e32 v67, 0xffff0000, v67
	v_and_b32_e32 v66, 0xffff0000, v66
	v_mov_b32_e32 v84, v83
	v_pk_mul_f32 v[76:77], v[78:79], v[76:77]
	v_bfe_u32 v0, v69, 16, 1
	v_bfe_u32 v78, v68, 16, 1
	v_pk_mul_f32 v[66:67], v[84:85], v[66:67]
	v_add3_u32 v68, v68, v78, s26
	v_add3_u32 v0, v69, v0, s26
	v_cvt_pk_bf16_f32 v66, v74, v66
	v_cvt_pk_bf16_f32 v67, v75, v67
	v_mov_b64_e32 v[74:75], s[36:37]
	s_movk_i32 s0, 0x1800
	v_bfe_u32 v79, v76, 16, 1
	v_mad_i64_i32 v[74:75], s[0:1], v240, s0, v[74:75]
	s_mov_b32 s53, s80
	v_bfe_u32 v80, v77, 16, 1
	v_add3_u32 v76, v76, v79, s26
	v_lshl_add_u64 v[74:75], v[74:75], 0, s[52:53]
	v_mov_b32_e32 v151, v1
	v_add3_u32 v77, v77, v80, s26
	v_lshrrev_b32_e32 v76, 16, v76
	v_lshl_add_u64 v[74:75], v[74:75], 0, v[150:151]
	s_mov_b64 s[0:1], 0x15304800
	v_lshrrev_b32_e32 v69, 16, v77
	v_and_or_b32 v68, v68, s24, v76
	v_lshl_add_u64 v[76:77], v[74:75], 0, s[0:1]
	v_add_co_u32_e32 v74, vcc, 0x15304000, v74
	s_mov_b32 s12, s13
	s_nop 0
	v_addc_co_u32_e32 v75, vcc, 0, v75, vcc
	s_andn2_b64 vcc, exec, s[82:83]
	v_and_or_b32 v69, v0, s24, v69
	global_store_dwordx4 v[74:75], v[70:73], off offset:2048
	global_store_dwordx4 v[76:77], v[66:69], off offset:16
	s_cbranch_vccz .LBB0_545

; #define LAS __attribute__((address_space(3)))
; __device__ __forceinline__ unsigned pk2(float lo, float hi) { return f2bf(lo) | (f2bf(hi) << 16); }
; #define BF8_TO_F32(vw, lo, hi) const f32x4 lo = {bflo(vw.x), bfhi(vw.x), bflo(vw.y), bfhi(vw.y)}, hi = {bflo(vw.z), bfhi(vw.z), bflo(vw.w), bfhi(vw.w)}
; __device__ __forceinline__ void mix_phase(LAS unsigned char* lds, const Params& p, const int layer) {
;     ...
;                 for (int i = 0; i < 2; ++i) {
;                     const int rl = (tid >> 4) + 32 * i, r = r0N + rl, c = c0 + q16 * 8, t = (r - NP) & 7, bs = (r - NP) >> 3;
;                     f32x4 x0 = *(const LAS f32x4*)(CWL + q16 * 8), x1 = *(const LAS f32x4*)(CWL + q16 * 8 + 4);
; #pragma unroll
;                     for (int k = 0; k < 4; ++k) { const int jb = 3 - k;
;                         const f32x4 w0 = *(const LAS f32x4*)(CWL + (k + 1) * 128 + q16 * 8), w1 = *(const LAS f32x4*)(CWL + (k + 1) * 128 + q16 * 8 + 4);
;                         if (jb <= t) { const v4u vw = *(const v4u*)(PROJ + (size_t)(r - jb) * NC + C_UB + c); BF8_TO_F32(vw, a0, a1); x0 += w0 * a0; x1 += w1 * a1; }
;                         else { const float* sp = sconv + ((size_t)bs * 3 + (3 + t - jb)) * LW + c; x0 += w0 * *(const f32x4*)sp; x1 += w1 * *(const f32x4*)(sp + 4); }
;                     }
;                     *(LAS f32x4*)(XCN + rl * 132 + q16 * 8) = x0; *(LAS f32x4*)(XCN + rl * 132 + q16 * 8 + 4) = x1;
;                     v4u o; o.x = pk2(x0[0], x0[1]); o.y = pk2(x0[2], x0[3]); o.z = pk2(x1[0], x1[1]); o.w = pk2(x1[2], x1[3]);
;                     *(LAS v4u*)(AtN + rl * 136 + q16 * 8) = o;
;                 }
.LBB0_490:
	s_or_b64 exec, exec, s[50:51]
	s_waitcnt lgkmcnt(0)
	s_and_saveexec_b64 s[20:21], s[44:45]
	s_waitcnt vmcnt(0)
	v_lshlrev_b32_e32 v90, 16, v94
	v_and_b32_e32 v91, 0xffff0000, v94
	v_lshlrev_b32_e32 v92, 16, v95
	v_and_b32_e32 v93, 0xffff0000, v95
	v_lshlrev_b32_e32 v94, 16, v96
	v_and_b32_e32 v95, 0xffff0000, v96
	v_lshlrev_b32_e32 v96, 16, v97
	v_and_b32_e32 v97, 0xffff0000, v97
	s_mov_b64 exec, s[20:21]
	s_and_saveexec_b64 s[20:21], s[46:47]
	v_lshlrev_b32_e32 v106, 16, v110
	v_and_b32_e32 v107, 0xffff0000, v110
	v_lshlrev_b32_e32 v108, 16, v111
	v_and_b32_e32 v109, 0xffff0000, v111
	v_lshlrev_b32_e32 v110, 16, v112
	v_and_b32_e32 v111, 0xffff0000, v112
	v_lshlrev_b32_e32 v112, 16, v113
	v_and_b32_e32 v113, 0xffff0000, v113
	s_mov_b64 exec, s[20:21]
	s_and_saveexec_b64 s[20:21], s[48:49]
	v_lshlrev_b32_e32 v122, 16, v126
	v_and_b32_e32 v123, 0xffff0000, v126
	v_lshlrev_b32_e32 v124, 16, v127
	v_and_b32_e32 v125, 0xffff0000, v127
	v_lshlrev_b32_e32 v126, 16, v128
	v_and_b32_e32 v127, 0xffff0000, v128
	v_lshlrev_b32_e32 v128, 16, v129
	v_and_b32_e32 v129, 0xffff0000, v129
	s_mov_b64 exec, s[20:21]
	v_pk_fma_f32 v[74:75], v[82:83], v[94:95], v[74:75]
	v_mov_b64_e32 v[82:83], s[74:75]
	s_xor_b64 s[86:87], s[0:1], -1
	v_mad_i64_i32 v[82:83], s[0:1], v171, s25, v[82:83]
	v_lshl_add_u64 v[82:83], v[82:83], 0, v[0:1]
	s_movk_i32 s0, 0x1000
	v_pk_fma_f32 v[80:81], v[88:89], v[92:93], v[80:81]
	v_pk_fma_f32 v[78:79], v[86:87], v[90:91], v[78:79]
	v_pk_fma_f32 v[76:77], v[84:85], v[96:97], v[76:77]
	v_add_co_u32_e32 v82, vcc, s0, v82
	v_pk_fma_f32 v[80:81], v[104:105], v[108:109], v[80:81]
	v_pk_fma_f32 v[78:79], v[102:103], v[106:107], v[78:79]
	v_pk_fma_f32 v[76:77], v[100:101], v[112:113], v[76:77]
	v_pk_fma_f32 v[74:75], v[98:99], v[110:111], v[74:75]
	v_addc_co_u32_e32 v83, vcc, 0, v83, vcc
	v_pk_fma_f32 v[86:87], v[120:121], v[124:125], v[80:81]
	v_pk_fma_f32 v[88:89], v[118:119], v[122:123], v[78:79]
	v_pk_fma_f32 v[90:91], v[116:117], v[128:129], v[76:77]
	v_pk_fma_f32 v[92:93], v[114:115], v[126:127], v[74:75]
	ds_read_b128 v[74:77], v233 offset:2048
	ds_read_b128 v[78:81], v233 offset:2064
	global_load_dwordx4 v[82:85], v[82:83], off
	s_movk_i32 s0, 0x210
	s_mov_b32 s17, 32
	s_andn2_b64 vcc, exec, s[86:87]
	s_waitcnt lgkmcnt(0)
	s_waitcnt vmcnt(0)
	v_lshlrev_b32_e32 v96, 16, v82
	v_and_b32_e32 v97, 0xffff0000, v82
	v_lshlrev_b32_e32 v82, 16, v83
	v_and_b32_e32 v83, 0xffff0000, v83
	v_pk_fma_f32 v[74:75], v[74:75], v[96:97], v[88:89]
	v_lshlrev_b32_e32 v94, 16, v84
	v_and_b32_e32 v95, 0xffff0000, v84
	v_lshlrev_b32_e32 v84, 16, v85
	v_and_b32_e32 v85, 0xffff0000, v85
	v_pk_fma_f32 v[76:77], v[76:77], v[82:83], v[86:87]
	v_mad_u64_u32 v[82:83], s[0:1], v159, s0, v[198:199]
	v_pk_fma_f32 v[80:81], v[80:81], v[84:85], v[90:91]
	v_pk_fma_f32 v[78:79], v[78:79], v[94:95], v[92:93]
	ds_write_b128 v82, v[74:77]
	ds_write_b128 v82, v[78:81] offset:16
	v_cvt_pk_bf16_f32 v74, v74, v75
	v_cvt_pk_bf16_f32 v75, v76, v77
	v_cvt_pk_bf16_f32 v76, v78, v79
	s_movk_i32 s0, 0x110
	v_cvt_pk_bf16_f32 v77, v80, v81
	v_mad_u64_u32 v[78:79], s[0:1], v159, s0, v[208:209]
	s_mov_b64 s[0:1], 0
	ds_write_b128 v78, v[74:77]
	s_cbranch_vccz .LBB0_503

; #define LAS __attribute__((address_space(3)))
; __device__ __forceinline__ unsigned pk2(float lo, float hi) { return f2bf(lo) | (f2bf(hi) << 16); }
; #define BF8_TO_F32(vw, lo, hi) const f32x4 lo = {bflo(vw.x), bfhi(vw.x), bflo(vw.y), bfhi(vw.y)}, hi = {bflo(vw.z), bfhi(vw.z), bflo(vw.w), bfhi(vw.w)}
; __device__ __forceinline__ void mix_phase(LAS unsigned char* lds, const Params& p, const int layer) {
;     ...
;             if (prtN) {
;                 const f32x4 cb0 = *(const LAS f32x4*)(CWL + q16 * 8), cb1 = *(const LAS f32x4*)(CWL + q16 * 8 + 4);
; #pragma unroll
;                 for (int i = 0; i < 2; ++i) {
;                     const int rl = (tid >> 4) + 32 * i, t = (r0N + rl) & 2047;
;                     f32x4 x0 = cb0, x1 = cb1;
; #pragma unroll
;                     for (int k = 0; k < 4; ++k) { const float f = ((3 - k) <= t) ? 1.0f : 0.0f;
;                         const f32x4 w0 = *(const LAS f32x4*)(CWL + (k + 1) * 128 + q16 * 8), w1 = *(const LAS f32x4*)(CWL + (k + 1) * 128 + q16 * 8 + 4);
;                         BF8_TO_F32(pre[i][k], a0, a1); x0 += w0 * (a0 * f); x1 += w1 * (a1 * f); }
;                     *(LAS f32x4*)(XCN + rl * 132 + q16 * 8) = x0; *(LAS f32x4*)(XCN + rl * 132 + q16 * 8 + 4) = x1;
;                     v4u o; o.x = pk2(x0[0], x0[1]); o.y = pk2(x0[2], x0[3]); o.z = pk2(x1[0], x1[1]); o.w = pk2(x1[2], x1[3]);
;                     *(LAS v4u*)(AtN + rl * 136 + q16 * 8) = o;
;                 }
.LBB0_504:
	s_and_b64 vcc, exec, s[20:21]
	s_cbranch_vccz .LBB0_506
	ds_read_b128 v[74:77], v233
	ds_read_b128 v[78:81], v233 offset:16
	v_and_b32_e32 v106, 0x7ff, v153
	ds_read_b128 v[82:85], v233 offset:512
	ds_read_b128 v[86:89], v233 offset:528
	v_cmp_gt_u32_e32 vcc, 3, v106
	v_lshlrev_b32_e32 v90, 16, v34
	v_and_b32_e32 v91, 0xffff0000, v34
	v_cndmask_b32_e64 v0, 1.0, 0, vcc
	v_lshlrev_b32_e32 v92, 16, v35
	v_and_b32_e32 v93, 0xffff0000, v35
	v_lshlrev_b32_e32 v94, 16, v36
	v_and_b32_e32 v95, 0xffff0000, v36
	v_lshlrev_b32_e32 v96, 16, v37
	v_and_b32_e32 v97, 0xffff0000, v37
	v_pk_mul_f32 v[92:93], v[0:1], v[92:93] op_sel_hi:[0,1]
	v_pk_mul_f32 v[90:91], v[0:1], v[90:91] op_sel_hi:[0,1]
	s_waitcnt lgkmcnt(0)
	v_pk_fma_f32 v[90:91], v[90:91], v[82:83], v[74:75]
	v_pk_fma_f32 v[92:93], v[92:93], v[84:85], v[76:77]
	v_pk_mul_f32 v[82:83], v[0:1], v[96:97] op_sel_hi:[0,1]
	v_pk_mul_f32 v[84:85], v[0:1], v[94:95] op_sel_hi:[0,1]
	v_pk_fma_f32 v[94:95], v[84:85], v[86:87], v[78:79]
	v_pk_fma_f32 v[96:97], v[82:83], v[88:89], v[80:81]
	ds_read_b128 v[82:85], v233 offset:1024
	ds_read_b128 v[86:89], v233 offset:1040
	v_cmp_gt_u32_e32 vcc, 2, v106
	v_lshlrev_b32_e32 v98, 16, v38
	v_and_b32_e32 v99, 0xffff0000, v38
	v_cndmask_b32_e64 v0, 1.0, 0, vcc
	v_lshlrev_b32_e32 v100, 16, v39
	v_and_b32_e32 v101, 0xffff0000, v39
	v_lshlrev_b32_e32 v102, 16, v40
	v_and_b32_e32 v103, 0xffff0000, v40
	v_lshlrev_b32_e32 v104, 16, v41
	v_and_b32_e32 v105, 0xffff0000, v41
	v_pk_mul_f32 v[98:99], v[0:1], v[98:99] op_sel_hi:[0,1]
	v_pk_mul_f32 v[100:101], v[0:1], v[100:101] op_sel_hi:[0,1]
	s_waitcnt lgkmcnt(0)
	v_pk_fma_f32 v[92:93], v[100:101], v[84:85], v[92:93]
	v_pk_fma_f32 v[90:91], v[98:99], v[82:83], v[90:91]
	v_pk_mul_f32 v[82:83], v[0:1], v[102:103] op_sel_hi:[0,1]
	v_pk_mul_f32 v[84:85], v[0:1], v[104:105] op_sel_hi:[0,1]
	v_pk_fma_f32 v[96:97], v[84:85], v[88:89], v[96:97]
	v_pk_fma_f32 v[94:95], v[82:83], v[86:87], v[94:95]
	ds_read_b128 v[82:85], v233 offset:1536
	ds_read_b128 v[86:89], v233 offset:1552
	v_cmp_eq_u32_e32 vcc, 0, v106
	v_lshlrev_b32_e32 v98, 16, v42
	v_and_b32_e32 v99, 0xffff0000, v42
	v_cndmask_b32_e64 v0, 1.0, 0, vcc
	v_lshlrev_b32_e32 v100, 16, v43
	v_and_b32_e32 v101, 0xffff0000, v43
	v_lshlrev_b32_e32 v102, 16, v44
	v_and_b32_e32 v103, 0xffff0000, v44
	v_lshlrev_b32_e32 v104, 16, v45
	v_and_b32_e32 v105, 0xffff0000, v45
	v_pk_mul_f32 v[100:101], v[0:1], v[100:101] op_sel_hi:[0,1]
	v_pk_mul_f32 v[98:99], v[0:1], v[98:99] op_sel_hi:[0,1]
	s_waitcnt lgkmcnt(0)
	v_pk_fma_f32 v[90:91], v[98:99], v[82:83], v[90:91]
	v_pk_fma_f32 v[92:93], v[100:101], v[84:85], v[92:93]
	v_pk_mul_f32 v[82:83], v[0:1], v[104:105] op_sel_hi:[0,1]
	v_pk_mul_f32 v[84:85], v[0:1], v[102:103] op_sel_hi:[0,1]
	v_pk_fma_f32 v[94:95], v[84:85], v[86:87], v[94:95]
	v_pk_fma_f32 v[96:97], v[82:83], v[88:89], v[96:97]
	ds_read_b128 v[82:85], v233 offset:2048
	ds_read_b128 v[86:89], v233 offset:2064
	v_lshlrev_b32_e32 v98, 16, v46
	v_and_b32_e32 v99, 0xffff0000, v46
	v_lshlrev_b32_e32 v100, 16, v47
	v_and_b32_e32 v101, 0xffff0000, v47
	s_waitcnt lgkmcnt(0)
; #define LAS __attribute__((address_space(3)))
; __device__ __forceinline__ unsigned pk2(float lo, float hi) { return f2bf(lo) | (f2bf(hi) << 16); }
; #define BF8_TO_F32(vw, lo, hi) const f32x4 lo = {bflo(vw.x), bfhi(vw.x), bflo(vw.y), bfhi(vw.y)}, hi = {bflo(vw.z), bfhi(vw.z), bflo(vw.w), bfhi(vw.w)}
; __device__ __forceinline__ void mix_phase(LAS unsigned char* lds, const Params& p, const int layer) {
;     ...
;                 for (int i = 0; i < 2; ++i) {
;                     const int rl = (tid >> 4) + 32 * i, t = (r0N + rl) & 2047;
;                     f32x4 x0 = cb0, x1 = cb1;
; #pragma unroll
;                     for (int k = 0; k < 4; ++k) { const float f = ((3 - k) <= t) ? 1.0f : 0.0f;
;                         const f32x4 w0 = *(const LAS f32x4*)(CWL + (k + 1) * 128 + q16 * 8), w1 = *(const LAS f32x4*)(CWL + (k + 1) * 128 + q16 * 8 + 4);
;                         BF8_TO_F32(pre[i][k], a0, a1); x0 += w0 * (a0 * f); x1 += w1 * (a1 * f); }
;                     *(LAS f32x4*)(XCN + rl * 132 + q16 * 8) = x0; *(LAS f32x4*)(XCN + rl * 132 + q16 * 8 + 4) = x1;
;                     v4u o; o.x = pk2(x0[0], x0[1]); o.y = pk2(x0[2], x0[3]); o.z = pk2(x1[0], x1[1]); o.w = pk2(x1[2], x1[3]);
;                     *(LAS v4u*)(AtN + rl * 136 + q16 * 8) = o;
;                 }
	v_pk_fma_f32 v[82:83], v[82:83], v[98:99], v[90:91]
	v_lshlrev_b32_e32 v102, 16, v48
	v_and_b32_e32 v103, 0xffff0000, v48
	v_lshlrev_b32_e32 v104, 16, v49
	v_and_b32_e32 v105, 0xffff0000, v49
	v_pk_fma_f32 v[84:85], v[84:85], v[100:101], v[92:93]
	v_add3_u32 v98, s15, v131, v236
	v_pk_fma_f32 v[88:89], v[88:89], v[104:105], v[96:97]
	v_pk_fma_f32 v[86:87], v[86:87], v[102:103], v[94:95]
	ds_write_b128 v98, v[82:85]
	ds_write_b128 v98, v[86:89] offset:16
	v_cvt_pk_bf16_f32 v82, v82, v83
	v_cvt_pk_bf16_f32 v83, v84, v85
	v_cvt_pk_bf16_f32 v84, v86, v87
	v_cvt_pk_bf16_f32 v85, v88, v89
	v_add3_u32 v99, s14, v138, v141
	ds_write_b128 v99, v[82:85]
	v_add_u32_e32 v0, 32, v153
	v_and_b32_e32 v100, 0x7ff, v0
	ds_read_b128 v[82:85], v233 offset:512
	ds_read_b128 v[86:89], v233 offset:528
	v_cmp_gt_u32_e32 vcc, 3, v100
	v_lshlrev_b32_e32 v90, 16, v50
	v_and_b32_e32 v91, 0xffff0000, v50
	v_cndmask_b32_e64 v0, 1.0, 0, vcc
	v_lshlrev_b32_e32 v92, 16, v51
	v_and_b32_e32 v93, 0xffff0000, v51
	v_lshlrev_b32_e32 v94, 16, v52
	v_and_b32_e32 v95, 0xffff0000, v52
	v_lshlrev_b32_e32 v96, 16, v53
	v_and_b32_e32 v97, 0xffff0000, v53
	v_pk_mul_f32 v[90:91], v[0:1], v[90:91] op_sel_hi:[0,1]
	v_pk_mul_f32 v[92:93], v[0:1], v[92:93] op_sel_hi:[0,1]
	s_waitcnt lgkmcnt(0)
	v_pk_fma_f32 v[84:85], v[92:93], v[84:85], v[76:77]
	v_pk_fma_f32 v[82:83], v[90:91], v[82:83], v[74:75]
	v_pk_mul_f32 v[74:75], v[0:1], v[94:95] op_sel_hi:[0,1]
	v_pk_mul_f32 v[76:77], v[0:1], v[96:97] op_sel_hi:[0,1]
	v_pk_fma_f32 v[88:89], v[76:77], v[88:89], v[80:81]
	v_pk_fma_f32 v[86:87], v[74:75], v[86:87], v[78:79]
	ds_read_b128 v[74:77], v233 offset:1024
	ds_read_b128 v[78:81], v233 offset:1040
	v_cmp_gt_u32_e32 vcc, 2, v100
	v_lshlrev_b32_e32 v90, 16, v54
	v_and_b32_e32 v91, 0xffff0000, v54
	v_cndmask_b32_e64 v0, 1.0, 0, vcc
	v_lshlrev_b32_e32 v92, 16, v55
	v_and_b32_e32 v93, 0xffff0000, v55
	v_lshlrev_b32_e32 v94, 16, v56
	v_and_b32_e32 v95, 0xffff0000, v56
	v_lshlrev_b32_e32 v96, 16, v57
	v_and_b32_e32 v97, 0xffff0000, v57
	v_pk_mul_f32 v[92:93], v[0:1], v[92:93] op_sel_hi:[0,1]
	v_pk_mul_f32 v[90:91], v[0:1], v[90:91] op_sel_hi:[0,1]
	s_waitcnt lgkmcnt(0)
	v_pk_fma_f32 v[82:83], v[90:91], v[74:75], v[82:83]
	v_pk_fma_f32 v[84:85], v[92:93], v[76:77], v[84:85]
	v_pk_mul_f32 v[74:75], v[0:1], v[96:97] op_sel_hi:[0,1]
	v_pk_mul_f32 v[76:77], v[0:1], v[94:95] op_sel_hi:[0,1]
	v_pk_fma_f32 v[86:87], v[76:77], v[78:79], v[86:87]
	v_pk_fma_f32 v[88:89], v[74:75], v[80:81], v[88:89]
	ds_read_b128 v[74:77], v233 offset:1536
	ds_read_b128 v[78:81], v233 offset:1552
	v_cmp_eq_u32_e32 vcc, 0, v100
	v_lshlrev_b32_e32 v90, 16, v58
	v_and_b32_e32 v91, 0xffff0000, v58
	v_cndmask_b32_e64 v0, 1.0, 0, vcc
	v_lshlrev_b32_e32 v92, 16, v59
	v_and_b32_e32 v93, 0xffff0000, v59
	v_lshlrev_b32_e32 v94, 16, v60
	v_and_b32_e32 v95, 0xffff0000, v60
	v_lshlrev_b32_e32 v96, 16, v61
	v_and_b32_e32 v97, 0xffff0000, v61
	v_pk_mul_f32 v[90:91], v[0:1], v[90:91] op_sel_hi:[0,1]
	v_pk_mul_f32 v[92:93], v[0:1], v[92:93] op_sel_hi:[0,1]
	s_waitcnt lgkmcnt(0)
	v_pk_fma_f32 v[84:85], v[92:93], v[76:77], v[84:85]
	v_pk_fma_f32 v[82:83], v[90:91], v[74:75], v[82:83]
	v_pk_mul_f32 v[74:75], v[0:1], v[94:95] op_sel_hi:[0,1]
	v_pk_mul_f32 v[76:77], v[0:1], v[96:97] op_sel_hi:[0,1]
	v_pk_fma_f32 v[88:89], v[76:77], v[80:81], v[88:89]
	v_pk_fma_f32 v[86:87], v[74:75], v[78:79], v[86:87]
	ds_read_b128 v[74:77], v233 offset:2048
	ds_read_b128 v[78:81], v233 offset:2064
	v_lshlrev_b32_e32 v90, 16, v62
	v_and_b32_e32 v91, 0xffff0000, v62
	v_lshlrev_b32_e32 v92, 16, v63
	v_and_b32_e32 v93, 0xffff0000, v63
	s_waitcnt lgkmcnt(0)
	v_pk_fma_f32 v[74:75], v[74:75], v[90:91], v[82:83]
	v_lshlrev_b32_e32 v94, 16, v64
	v_and_b32_e32 v95, 0xffff0000, v64
	v_lshlrev_b32_e32 v96, 16, v65
	v_and_b32_e32 v97, 0xffff0000, v65
	v_pk_fma_f32 v[76:77], v[76:77], v[92:93], v[84:85]
	v_pk_fma_f32 v[78:79], v[78:79], v[94:95], v[86:87]
	v_pk_fma_f32 v[80:81], v[80:81], v[96:97], v[88:89]
	ds_write_b128 v98, v[74:77] offset:16896
	ds_write_b128 v98, v[78:81] offset:16912
	v_cvt_pk_bf16_f32 v74, v74, v75
	v_cvt_pk_bf16_f32 v75, v76, v77
	v_cvt_pk_bf16_f32 v76, v78, v79
	v_cvt_pk_bf16_f32 v77, v80, v81
	ds_write_b128 v99, v[74:77] offset:8704

; #define LAS __attribute__((address_space(3)))
; __device__ __forceinline__ unsigned pk2(float lo, float hi) { return f2bf(lo) | (f2bf(hi) << 16); }
; __device__ __forceinline__ void mix_phase(LAS unsigned char* lds, const Params& p, const int layer) {
;     ...
;             for (int i = 0; i < 2; ++i) {
;                 const int rl = (tid >> 5) + 16 * i, bi = prt ? rl + 15 : (rl >> 3) * 23 + 15 + (rl & 7), t = (r0 + rl) & 2047;
;                 const LAS float* sp = SL + bi * 264 + q * 8;
;                 const f32x4 u0 = *(const LAS f32x4*)sp, u1 = *(const LAS f32x4*)(sp + 4);
;                 f32x4 s0 = u0, s1 = u1;
; #pragma unroll 4
;                 for (int j = 1; j < w; ++j) { s0 += *(const LAS f32x4*)(sp - j * 264); s1 += *(const LAS f32x4*)(sp - j * 264 + 4); }
;                 const int cnt = (prt && t + 1 < w) ? t + 1 : w; const float inv = 1.0f / (float)cnt;
;                 const f32x4 d0 = s0 * inv - u0, d1 = s1 * inv - u1;
;                 v4u o; o.x = pk2(d0[0], d0[1]); o.y = pk2(d0[2], d0[3]); o.z = pk2(d1[0], d1[1]); o.w = pk2(d1[2], d1[3]);
;                 *(LAS v4u*)(At + rl * 264 + q * 8) = o;
;             }
;             __syncthreads();
.Lpw_tail_a:
	ds_read_b128 v[150:153], v149 offset:1056
	ds_read_b128 v[154:157], v0 offset:1056
	v_add_u32_e32 v0, v141, v119
	ds_read_b128 v[158:161], v141
	ds_read_b128 v[252:255], v0
	s_waitcnt lgkmcnt(2)
	v_pk_add_f32 v[100:101], v[100:101], v[152:153]
	v_pk_add_f32 v[98:99], v[98:99], v[150:151]
	v_pk_add_f32 v[96:97], v[96:97], v[156:157]
	v_pk_add_f32 v[94:95], v[94:95], v[154:155]
	v_mov_b32_e32 v0, v142
	v_pk_fma_f32 v[90:91], v[0:1], v[98:99], v[90:91] op_sel_hi:[0,1,1] neg_lo:[0,0,1] neg_hi:[0,0,1]
	v_pk_fma_f32 v[92:93], v[0:1], v[100:101], v[92:93] op_sel_hi:[0,1,1] neg_lo:[0,0,1] neg_hi:[0,0,1]
	v_pk_fma_f32 v[86:87], v[0:1], v[94:95], v[86:87] op_sel_hi:[0,1,1] neg_lo:[0,0,1] neg_hi:[0,0,1]
	v_pk_fma_f32 v[88:89], v[0:1], v[96:97], v[88:89] op_sel_hi:[0,1,1] neg_lo:[0,0,1] neg_hi:[0,0,1]
	v_cvt_pk_bf16_f32 v90, v90, v91
	v_cvt_pk_bf16_f32 v91, v92, v93
	v_cvt_pk_bf16_f32 v92, v86, v87
	v_cvt_pk_bf16_f32 v93, v88, v89
	v_lshrrev_b32_e32 v0, 1, v118
	v_add_u32_e32 v149, v146, v0
	v_ashrrev_i32_e32 v0, 1, v119
	v_add_u32_e32 v0, v149, v0
	ds_write_b64 v149, v[90:91]
	ds_write_b64 v0, v[92:93]
	s_waitcnt lgkmcnt(2)
	v_pk_add_f32 v[98:99], v[98:99], v[158:159]
	v_pk_add_f32 v[100:101], v[100:101], v[160:161]
	v_pk_add_f32 v[94:95], v[94:95], v[252:253]
	v_pk_add_f32 v[96:97], v[96:97], v[254:255]
	v_pk_add_f32 v[98:99], v[98:99], v[150:151] neg_lo:[0,1] neg_hi:[0,1]
	v_pk_add_f32 v[100:101], v[100:101], v[152:153] neg_lo:[0,1] neg_hi:[0,1]
	v_pk_add_f32 v[94:95], v[94:95], v[154:155] neg_lo:[0,1] neg_hi:[0,1]
	v_pk_add_f32 v[96:97], v[96:97], v[156:157] neg_lo:[0,1] neg_hi:[0,1]
	v_mov_b32_e32 v0, v143
	v_pk_fma_f32 v[158:159], v[0:1], v[98:99], v[158:159] op_sel_hi:[0,1,1] neg_lo:[0,0,1] neg_hi:[0,0,1]
	v_pk_fma_f32 v[160:161], v[0:1], v[100:101], v[160:161] op_sel_hi:[0,1,1] neg_lo:[0,0,1] neg_hi:[0,0,1]
	v_pk_fma_f32 v[252:253], v[0:1], v[94:95], v[252:253] op_sel_hi:[0,1,1] neg_lo:[0,0,1] neg_hi:[0,0,1]
	v_pk_fma_f32 v[254:255], v[0:1], v[96:97], v[254:255] op_sel_hi:[0,1,1] neg_lo:[0,0,1] neg_hi:[0,0,1]
	v_cvt_pk_bf16_f32 v158, v158, v159
	v_cvt_pk_bf16_f32 v159, v160, v161
	v_cvt_pk_bf16_f32 v160, v252, v253
	v_cvt_pk_bf16_f32 v161, v254, v255
	v_lshrrev_b32_e32 v0, 1, v118
	v_add_u32_e32 v149, v147, v0
	v_ashrrev_i32_e32 v0, 1, v119
	v_add_u32_e32 v0, v149, v0
	ds_write_b64 v149, v[158:159]
	ds_write_b64 v0, v[160:161]
	s_waitcnt lgkmcnt(0)
	s_barrier
; #define LAS __attribute__((address_space(3)))
; __device__ __forceinline__ unsigned pk2(float lo, float hi) { return f2bf(lo) | (f2bf(hi) << 16); }
; __device__ __forceinline__ float bflo(unsigned w) { return __uint_as_float(w << 16); }
; __device__ __forceinline__ float bfhi(unsigned w) { return __uint_as_float(w & 0xffff0000u); }
; __device__ __forceinline__ void mix_phase(LAS unsigned char* lds, const Params& p, const int layer) {
;     ...
; #pragma unroll
;             for (int ks = 0; ks < 8; ++ks) {
;                 bf16x8 a[2];
; #pragma unroll
;                 for (int m = 0; m < 2; ++m) a[m] = *(const LAS bf16x8*)(At + (m * 16 + fr) * 264 + ks * 32 + fq * 8);
; #pragma unroll
;                 for (int m = 0; m < 2; ++m)
; #pragma unroll
;                     for (int n = 0; n < 2; ++n) acc[m][n] = __builtin_amdgcn_mfma_f32_16x16x32_bf16(b[n][ks], a[m], acc[m][n], 0, 0, 0);
;             }
;             bf16* YA = (bf16*)(ws + WS_YA);
; #pragma unroll
;             for (int m = 0; m < 2; ++m)
; #pragma unroll
;                 for (int n = 0; n < 2; ++n) { const int r = r0 + m * 16 + fr, ch = g * 256 + wid * 32 + n * 16 + fq * 4; const v2u sg = sgc[m][n];
;                     const f32x4 y = acc[m][n] * ps[n] * (f32x4){bflo(sg.x), bfhi(sg.x), bflo(sg.y), bfhi(sg.y)};
;                     v2u o; o.x = pk2(y[0], y[1]); o.y = pk2(y[2], y[3]); *(v2u*)(YA + (size_t)r * KCAT + ch) = o; }
	ds_read_b128 v[86:89], v148
	ds_read_b128 v[90:93], v148 offset:8448
	ds_read_b128 v[150:153], v148 offset:64
	ds_read_b128 v[154:157], v148 offset:8512
	s_waitcnt lgkmcnt(0)
	s_waitcnt vmcnt(15)
	v_mfma_f32_16x16x32_bf16 v[94:97], v[42:45], v[86:89], 0
	v_or_b32_e32 v0, s7, v135
	s_movk_i32 s12, 0x1800
	s_and_b64 vcc, exec, s[90:91]
	v_mfma_f32_16x16x32_bf16 v[86:89], v[74:77], v[86:89], 0
	v_mfma_f32_16x16x32_bf16 v[98:101], v[42:45], v[90:93], 0
	v_mfma_f32_16x16x32_bf16 v[90:93], v[74:77], v[90:93], 0
	v_mfma_f32_16x16x32_bf16 v[94:97], v[38:41], v[150:153], v[94:97]
	v_mfma_f32_16x16x32_bf16 v[86:89], v[70:73], v[150:153], v[86:89]
	v_mfma_f32_16x16x32_bf16 v[98:101], v[38:41], v[154:157], v[98:101]
	v_mfma_f32_16x16x32_bf16 v[90:93], v[70:73], v[154:157], v[90:93]
	ds_read_b128 v[150:153], v148 offset:128
	ds_read_b128 v[154:157], v148 offset:8576
	s_waitcnt lgkmcnt(1)
	v_mfma_f32_16x16x32_bf16 v[94:97], v[34:37], v[150:153], v[94:97]
	v_mfma_f32_16x16x32_bf16 v[86:89], v[66:69], v[150:153], v[86:89]
	s_waitcnt lgkmcnt(0)
	v_mfma_f32_16x16x32_bf16 v[98:101], v[34:37], v[154:157], v[98:101]
	v_mfma_f32_16x16x32_bf16 v[90:93], v[66:69], v[154:157], v[90:93]
	ds_read_b128 v[150:153], v148 offset:192
	ds_read_b128 v[154:157], v148 offset:8640
	s_waitcnt lgkmcnt(1)
	v_mfma_f32_16x16x32_bf16 v[94:97], v[30:33], v[150:153], v[94:97]
	s_waitcnt vmcnt(10)
	v_mfma_f32_16x16x32_bf16 v[86:89], v[62:65], v[150:153], v[86:89]
	s_waitcnt lgkmcnt(0)
	v_mfma_f32_16x16x32_bf16 v[98:101], v[30:33], v[154:157], v[98:101]
	v_mfma_f32_16x16x32_bf16 v[90:93], v[62:65], v[154:157], v[90:93]
	ds_read_b128 v[150:153], v148 offset:256
	ds_read_b128 v[154:157], v148 offset:8704
	s_waitcnt lgkmcnt(1)
	v_mfma_f32_16x16x32_bf16 v[94:97], v[26:29], v[150:153], v[94:97]
	v_mfma_f32_16x16x32_bf16 v[86:89], v[58:61], v[150:153], v[86:89]
	s_waitcnt lgkmcnt(0)
	v_mfma_f32_16x16x32_bf16 v[98:101], v[26:29], v[154:157], v[98:101]
	v_mfma_f32_16x16x32_bf16 v[90:93], v[58:61], v[154:157], v[90:93]
	ds_read_b128 v[150:153], v148 offset:320
	ds_read_b128 v[154:157], v148 offset:8768
	s_waitcnt lgkmcnt(1)
	v_mfma_f32_16x16x32_bf16 v[94:97], v[22:25], v[150:153], v[94:97]
	v_mfma_f32_16x16x32_bf16 v[86:89], v[54:57], v[150:153], v[86:89]
	s_waitcnt lgkmcnt(0)
	v_mfma_f32_16x16x32_bf16 v[98:101], v[22:25], v[154:157], v[98:101]
	v_mfma_f32_16x16x32_bf16 v[90:93], v[54:57], v[154:157], v[90:93]
	ds_read_b128 v[150:153], v148 offset:384
	ds_read_b128 v[154:157], v148 offset:8832
	s_waitcnt lgkmcnt(1)
	v_mfma_f32_16x16x32_bf16 v[94:97], v[18:21], v[150:153], v[94:97]
	v_mfma_f32_16x16x32_bf16 v[86:89], v[50:53], v[150:153], v[86:89]
	s_waitcnt lgkmcnt(0)
	v_mfma_f32_16x16x32_bf16 v[98:101], v[18:21], v[154:157], v[98:101]
	v_mfma_f32_16x16x32_bf16 v[90:93], v[50:53], v[154:157], v[90:93]
	ds_read_b128 v[150:153], v148 offset:448
	ds_read_b128 v[154:157], v148 offset:8896
	s_waitcnt lgkmcnt(1)
	v_mfma_f32_16x16x32_bf16 v[94:97], v[14:17], v[150:153], v[94:97]
	s_waitcnt lgkmcnt(0)
	v_mfma_f32_16x16x32_bf16 v[98:101], v[14:17], v[154:157], v[98:101]
	s_nop 5
	v_mul_f32_e64 v94, v82, v94
	v_mul_f32_e64 v95, v83, v95
	v_pk_mul_f32 v[96:97], v[84:85], v[96:97]
	v_mfma_f32_16x16x32_bf16 v[90:93], v[46:49], v[154:157], v[90:93]
	s_waitcnt vmcnt(7)
	v_lshlrev_b32_e32 v156, 16, v108
	v_and_b32_e32 v157, 0xffff0000, v108
	v_lshlrev_b32_e32 v108, 16, v109
	v_and_b32_e32 v109, 0xffff0000, v109
	v_pk_mul_f32 v[94:95], v[94:95], v[156:157]
	v_pk_mul_f32 v[96:97], v[96:97], v[108:109]
	v_cvt_pk_bf16_f32 v94, v94, v95
	v_mfma_f32_16x16x32_bf16 v[86:89], v[46:49], v[150:153], v[86:89]
	v_add_u32_e32 v150, s6, v137
	v_mov_b64_e32 v[152:153], s[86:87]
	v_cvt_pk_bf16_f32 v95, v96, v97
	v_ashrrev_i32_e32 v151, 31, v150
	v_mad_i64_i32 v[154:155], s[6:7], v0, s12, v[152:153]
	v_lshlrev_b64 v[96:97], 1, v[150:151]
	v_lshl_add_u64 v[108:109], v[154:155], 0, v[96:97]
	global_store_dwordx2 v[108:109], v[94:95], off
	v_pk_mul_f32 v[86:87], v[78:79], v[86:87]
	s_waitcnt vmcnt(5)
	v_lshlrev_b32_e32 v94, 16, v106
	v_and_b32_e32 v95, 0xffff0000, v106
	v_pk_mul_f32 v[86:87], v[86:87], v[94:95]
	v_pk_mul_f32 v[88:89], v[80:81], v[88:89]
	v_lshlrev_b32_e32 v106, 16, v107
	v_and_b32_e32 v107, 0xffff0000, v107
	v_pk_mul_f32 v[88:89], v[88:89], v[106:107]
	v_cvt_pk_bf16_f32 v86, v86, v87
	v_cvt_pk_bf16_f32 v87, v88, v89
	v_pk_mul_f32 v[94:95], v[82:83], v[98:99]
	v_lshlrev_b32_e32 v98, 16, v104
	v_and_b32_e32 v99, 0xffff0000, v104
	v_or_b32_e32 v0, 16, v0
	v_pk_mul_f32 v[94:95], v[94:95], v[98:99]
	global_store_dwordx2 v[108:109], v[86:87], off offset:32
	v_mad_i64_i32 v[86:87], s[6:7], v0, s12, v[152:153]
	v_pk_mul_f32 v[88:89], v[84:85], v[100:101]
	v_lshlrev_b32_e32 v100, 16, v105
	v_and_b32_e32 v101, 0xffff0000, v105
	v_pk_mul_f32 v[88:89], v[88:89], v[100:101]
	v_cvt_pk_bf16_f32 v94, v94, v95
	v_cvt_pk_bf16_f32 v95, v88, v89
	v_pk_mul_f32 v[88:89], v[80:81], v[92:93]
	v_pk_mul_f32 v[90:91], v[78:79], v[90:91]
	v_lshlrev_b32_e32 v92, 16, v102
	v_and_b32_e32 v93, 0xffff0000, v102
	v_pk_mul_f32 v[90:91], v[90:91], v[92:93]
	v_lshl_add_u64 v[86:87], v[86:87], 0, v[96:97]
	global_store_dwordx2 v[86:87], v[94:95], off
	v_lshlrev_b32_e32 v94, 16, v103
	v_and_b32_e32 v95, 0xffff0000, v103
	v_pk_mul_f32 v[88:89], v[88:89], v[94:95]
	v_cvt_pk_bf16_f32 v90, v90, v91
	v_cvt_pk_bf16_f32 v91, v88, v89
	v_readlane_b32 s6, v249, 62
	s_add_i32 s2, s2, s6
	s_waitcnt vmcnt(4)
	v_mov_b64_e32 v[102:103], v[126:127]
	v_mov_b64_e32 v[104:105], v[124:125]
	s_waitcnt vmcnt(3)
	v_mov_b64_e32 v[106:107], v[128:129]
	v_mov_b64_e32 v[108:109], v[122:123]
	global_store_dwordx2 v[86:87], v[90:91], off offset:32
	s_cbranch_vccz .LBB0_551
